# MLA attention loop: row-sum accumulation with v_pk_add_f32 (8 packed adds instead of 16 scalar per half-step; MLA loop is VALU-issue-bound)
# baseline (speedup 1.0000x reference)
.Lm_goA:
	s_setprio 1
	s_waitcnt lgkmcnt(13)
	v_mfma_f32_32x32x16_bf16 v[50:65], v[182:185], v[82:85], v[34:49]
	v_exp_f32_e32 v66, v66
	v_exp_f32_e32 v67, v67
	v_exp_f32_e32 v68, v68
	s_waitcnt lgkmcnt(12)
	v_mfma_f32_32x32x16_bf16 v[50:65], v[186:189], v[86:89], v[50:65]
	v_exp_f32_e32 v69, v69
	v_exp_f32_e32 v70, v70
	v_exp_f32_e32 v71, v71
	v_cvt_pk_bf16_f32 v152, v66, v67
	s_waitcnt lgkmcnt(11)
	v_mfma_f32_32x32x16_bf16 v[50:65], v[190:193], v[90:93], v[50:65]
	v_exp_f32_e32 v72, v72
	v_exp_f32_e32 v73, v73
	v_exp_f32_e32 v74, v74
	v_cvt_pk_bf16_f32 v153, v68, v69
	v_cvt_pk_bf16_f32 v154, v70, v71
	s_waitcnt lgkmcnt(10)
	v_mfma_f32_32x32x16_bf16 v[50:65], v[202:205], v[94:97], v[50:65]
	v_exp_f32_e32 v75, v75
	v_exp_f32_e32 v76, v76
	v_exp_f32_e32 v77, v77
	v_cvt_pk_bf16_f32 v155, v72, v73
	s_waitcnt lgkmcnt(9)
	v_mfma_f32_32x32x16_bf16 v[50:65], v[206:209], v[98:101], v[50:65]
	v_exp_f32_e32 v78, v78
	v_exp_f32_e32 v79, v79
	v_cvt_pk_bf16_f32 v214, v74, v75
	v_cvt_pk_bf16_f32 v215, v76, v77
	s_waitcnt lgkmcnt(8)
	v_mfma_f32_32x32x16_bf16 v[50:65], v[210:213], v[102:105], v[50:65]
	v_exp_f32_e32 v80, v80
	v_exp_f32_e32 v81, v81
	v_cvt_pk_bf16_f32 v216, v78, v79
	v_cvt_pk_bf16_f32 v217, v80, v81
	s_waitcnt lgkmcnt(6)
	v_mfma_f32_32x32x16_bf16 v[2:17], v[118:121], v[152:155], v[2:17]
	v_pk_add_f32 v[218:219], v[66:67], v[68:69]
	v_pk_add_f32 v[218:219], v[218:219], v[70:71]
	v_pk_add_f32 v[218:219], v[218:219], v[72:73]
	s_waitcnt lgkmcnt(4)
	v_mfma_f32_32x32x16_bf16 v[18:33], v[122:125], v[152:155], v[18:33]
	v_pk_add_f32 v[218:219], v[218:219], v[74:75]
	v_pk_add_f32 v[218:219], v[218:219], v[76:77]
	ds_read_b128 v[182:185], v239 offset:6656
	ds_read_b128 v[186:189], v239 offset:6688
	ds_read_b128 v[190:193], v239 offset:6720
	ds_read_b128 v[202:205], v239 offset:6752
	ds_read_b128 v[206:209], v239 offset:6784
	ds_read_b128 v[210:213], v239 offset:6816
	s_waitcnt lgkmcnt(8)
	v_mfma_f32_32x32x16_bf16 v[2:17], v[144:147], v[214:217], v[2:17]
	v_pk_add_f32 v[218:219], v[218:219], v[78:79]
	v_pk_add_f32 v[218:219], v[218:219], v[80:81]
	v_max3_f32 v236, v50, v51, v52
	v_max3_f32 v237, v53, v54, v55
	s_waitcnt lgkmcnt(6)
	v_mfma_f32_32x32x16_bf16 v[18:33], v[148:151], v[214:217], v[18:33]
	s_setprio 0
	v_max3_f32 v236, v236, v56, v57
	v_max3_f32 v237, v237, v58, v59
	v_max3_f32 v236, v236, v60, v61
	v_max3_f32 v237, v237, v62, v63
	v_max3_f32 v236, v236, v64, v65
	v_max_f32_e32 v236, v236, v237
	v_cmp_lt_f32_e64 s[100:101], s61, v236
	ds_read_b64_tr_b16 v[220:221], v240 offset:19456
	ds_read_b64_tr_b16 v[222:223], v240 offset:20992
	ds_read_b64_tr_b16 v[224:225], v240 offset:19520
	ds_read_b64_tr_b16 v[226:227], v240 offset:21056
	ds_read_b64_tr_b16 v[228:229], v240 offset:22528
	ds_read_b64_tr_b16 v[230:231], v240 offset:24064
	ds_read_b64_tr_b16 v[232:233], v240 offset:22592
	ds_read_b64_tr_b16 v[234:235], v240 offset:24128
	v_add_f32_e32 v218, v218, v219
	v_add_f32_e32 v142, v142, v218
	s_cmp_lg_u64 s[100:101], 0
	s_cbranch_scc1 .Lm_rareB
.Lm_goB:
	s_setprio 1
	s_waitcnt lgkmcnt(13)
	v_mfma_f32_32x32x16_bf16 v[66:81], v[182:185], v[82:85], v[34:49]
	v_exp_f32_e32 v50, v50
	v_exp_f32_e32 v51, v51
	v_exp_f32_e32 v52, v52
	s_waitcnt lgkmcnt(12)
	v_mfma_f32_32x32x16_bf16 v[66:81], v[186:189], v[86:89], v[66:81]
	v_exp_f32_e32 v53, v53
	v_exp_f32_e32 v54, v54
	v_exp_f32_e32 v55, v55
	v_cvt_pk_bf16_f32 v152, v50, v51
	s_waitcnt lgkmcnt(11)
	v_mfma_f32_32x32x16_bf16 v[66:81], v[190:193], v[90:93], v[66:81]
	v_exp_f32_e32 v56, v56
	v_exp_f32_e32 v57, v57
	v_exp_f32_e32 v58, v58
	v_cvt_pk_bf16_f32 v153, v52, v53
	v_cvt_pk_bf16_f32 v154, v54, v55
	s_waitcnt lgkmcnt(10)
	v_mfma_f32_32x32x16_bf16 v[66:81], v[202:205], v[94:97], v[66:81]
	v_exp_f32_e32 v59, v59
	v_exp_f32_e32 v60, v60
	v_exp_f32_e32 v61, v61
	v_cvt_pk_bf16_f32 v155, v56, v57
	s_waitcnt lgkmcnt(9)
	v_mfma_f32_32x32x16_bf16 v[66:81], v[206:209], v[98:101], v[66:81]
	v_exp_f32_e32 v62, v62
	v_exp_f32_e32 v63, v63
	v_cvt_pk_bf16_f32 v214, v58, v59
	v_cvt_pk_bf16_f32 v215, v60, v61
	s_waitcnt lgkmcnt(8)
	v_mfma_f32_32x32x16_bf16 v[66:81], v[210:213], v[102:105], v[66:81]
	v_exp_f32_e32 v64, v64
	v_exp_f32_e32 v65, v65
	v_cvt_pk_bf16_f32 v216, v62, v63
	v_cvt_pk_bf16_f32 v217, v64, v65
	s_waitcnt lgkmcnt(6)
	v_mfma_f32_32x32x16_bf16 v[2:17], v[220:223], v[152:155], v[2:17]
	v_pk_add_f32 v[218:219], v[50:51], v[52:53]
	v_pk_add_f32 v[218:219], v[218:219], v[54:55]
	v_pk_add_f32 v[218:219], v[218:219], v[56:57]
	s_waitcnt lgkmcnt(4)
	v_mfma_f32_32x32x16_bf16 v[18:33], v[224:227], v[152:155], v[18:33]
	v_pk_add_f32 v[218:219], v[218:219], v[58:59]
	v_pk_add_f32 v[218:219], v[218:219], v[60:61]
	s_waitcnt lgkmcnt(2)
	v_mfma_f32_32x32x16_bf16 v[2:17], v[228:231], v[214:217], v[2:17]
	v_pk_add_f32 v[218:219], v[218:219], v[62:63]
	v_pk_add_f32 v[218:219], v[218:219], v[64:65]
	v_max3_f32 v236, v66, v67, v68
	v_max3_f32 v237, v69, v70, v71
	s_waitcnt lgkmcnt(0)
	v_mfma_f32_32x32x16_bf16 v[18:33], v[232:235], v[214:217], v[18:33]
	s_setprio 0
	v_max3_f32 v236, v236, v72, v73
	v_max3_f32 v237, v237, v74, v75
	v_max3_f32 v236, v236, v76, v77
	v_max3_f32 v237, v237, v78, v79
	v_max3_f32 v236, v236, v80, v81
	v_max_f32_e32 v236, v236, v237
	v_cmp_lt_f32_e64 s[100:101], s61, v236
	v_add_f32_e32 v218, v218, v219
	v_add_f32_e32 v142, v142, v218
	s_cmp_eq_u32 s0, 0xfc0000
	s_cbranch_scc1 .Lm_next
	s_xor_b32 s4, s11, 1
	s_mulk_i32 s4, 0x6400
	s_mov_b32 s6, s4
	v_add3_u32 v241, s6, v134, v133
	s_waitcnt vmcnt(1)
	ds_write_b128 v241, v[110:113]
	s_and_saveexec_b64 s[4:5], s[2:3]
	v_add3_u32 v241, s6, v135, v136
	ds_write_b128 v241, v[106:109] offset:128
	s_or_b64 exec, exec, s[4:5]
	v_add3_u32 v241, s6, v137, v133
	s_cmp_gt_u32 s10, 61
	s_waitcnt vmcnt(0)
	ds_write_b128 v241, v[114:117] offset:13312
	s_cbranch_scc1 .Lm_next
	v_lshl_add_u64 v[242:243], v[130:131], 0, s[0:1]
	v_add_co_u32_e32 v110, vcc, 0x150a0000, v242
	s_nop 1
	v_addc_co_u32_e32 v111, vcc, 0, v243, vcc
	global_load_dwordx4 v[110:113], v[110:111], off
	s_and_saveexec_b64 s[4:5], s[2:3]
	s_cbranch_execz .Lm_nok2
	global_load_dwordx4 v[106:109], v[128:129], off
